# attention: packed v_pk_mul_f32 rescale of the O accumulators (feeding the PV MFMAs SrcC) split into scalar v_mul_f32 pairs (bit-identical)
# speedup vs baseline: 1.0129x; 1.0034x over previous
.LBB0_545:
	v_mov_b32_e32 v206, v14
	s_nop 1
	v_permlane32_swap_b32_e32 v14, v206
	v_max3_f32 v14, v15, v14, v206
	v_cmp_gt_f32_e32 vcc, v14, v15
	s_cbranch_vccz .LBB0_547
	v_sub_f32_e32 v15, v15, v14
	v_exp_f32_e32 v206, v15
	s_nop 0
	v_mul_f32_e32 v0, v0, v206
	v_mul_f32_e32 v78, v206, v78
	v_mul_f32_e32 v79, v206, v79
	v_mul_f32_e32 v76, v206, v76
	v_mul_f32_e32 v77, v206, v77
	v_mul_f32_e32 v74, v206, v74
	v_mul_f32_e32 v75, v206, v75
	v_mul_f32_e32 v72, v206, v72
	v_mul_f32_e32 v73, v206, v73
	v_mul_f32_e32 v70, v206, v70
	v_mul_f32_e32 v71, v206, v71
	v_mul_f32_e32 v68, v206, v68
	v_mul_f32_e32 v69, v206, v69
	v_mul_f32_e32 v66, v206, v66
	v_mul_f32_e32 v67, v206, v67
	v_mul_f32_e32 v64, v206, v64
	v_mul_f32_e32 v65, v206, v65
	v_mul_f32_e32 v62, v206, v62
	v_mul_f32_e32 v63, v206, v63
	v_mul_f32_e32 v60, v206, v60
	v_mul_f32_e32 v61, v206, v61
	v_mul_f32_e32 v58, v206, v58
	v_mul_f32_e32 v59, v206, v59
	v_mul_f32_e32 v56, v206, v56
	v_mul_f32_e32 v57, v206, v57
	v_mul_f32_e32 v54, v206, v54
	v_mul_f32_e32 v55, v206, v55
	v_mul_f32_e32 v52, v206, v52
	v_mul_f32_e32 v53, v206, v53
	v_mul_f32_e32 v50, v206, v50
	v_mul_f32_e32 v51, v206, v51
	v_mul_f32_e32 v48, v206, v48
	v_mul_f32_e32 v49, v206, v49

.LBB0_552:
	v_mov_b32_e32 v148, v15
	s_nop 1
	v_permlane32_swap_b32_e32 v15, v148
	v_max3_f32 v15, v205, v15, v148
	v_cmp_gt_f32_e32 vcc, v15, v205
	s_cbranch_vccz .LBB0_554
	v_sub_f32_e32 v148, v205, v15
	v_exp_f32_e32 v148, v148
	s_nop 0
	v_mul_f32_e32 v192, v192, v148
	v_mul_f32_e32 v46, v148, v46
	v_mul_f32_e32 v47, v148, v47
	v_mul_f32_e32 v44, v148, v44
	v_mul_f32_e32 v45, v148, v45
	v_mul_f32_e32 v42, v148, v42
	v_mul_f32_e32 v43, v148, v43
	v_mul_f32_e32 v40, v148, v40
	v_mul_f32_e32 v41, v148, v41
	v_mul_f32_e32 v38, v148, v38
	v_mul_f32_e32 v39, v148, v39
	v_mul_f32_e32 v36, v148, v36
	v_mul_f32_e32 v37, v148, v37
	v_mul_f32_e32 v34, v148, v34
	v_mul_f32_e32 v35, v148, v35
	v_mul_f32_e32 v32, v148, v32
	v_mul_f32_e32 v33, v148, v33
	v_mul_f32_e32 v30, v148, v30
	v_mul_f32_e32 v31, v148, v31
	v_mul_f32_e32 v28, v148, v28
	v_mul_f32_e32 v29, v148, v29
	v_mul_f32_e32 v26, v148, v26
	v_mul_f32_e32 v27, v148, v27
	v_mul_f32_e32 v24, v148, v24
	v_mul_f32_e32 v25, v148, v25
	v_mul_f32_e32 v22, v148, v22
	v_mul_f32_e32 v23, v148, v23
	v_mul_f32_e32 v20, v148, v20
	v_mul_f32_e32 v21, v148, v21
	v_mul_f32_e32 v18, v148, v18
	v_mul_f32_e32 v19, v148, v19
	v_mul_f32_e32 v16, v148, v16
	v_mul_f32_e32 v17, v148, v17

.LBB0_561:
	v_mov_b32_e32 v206, v205
	s_nop 1
	v_permlane32_swap_b32_e32 v205, v206
	v_max3_f32 v205, v14, v205, v206
	v_cmp_gt_f32_e32 vcc, v205, v14
	s_cbranch_vccz .LBB0_563
	v_sub_f32_e32 v14, v14, v205
	v_exp_f32_e32 v14, v14
	s_nop 0
	v_mul_f32_e32 v0, v0, v14
	v_mul_f32_e32 v78, v14, v78
	v_mul_f32_e32 v79, v14, v79
	v_mul_f32_e32 v76, v14, v76
	v_mul_f32_e32 v77, v14, v77
	v_mul_f32_e32 v74, v14, v74
	v_mul_f32_e32 v75, v14, v75
	v_mul_f32_e32 v72, v14, v72
	v_mul_f32_e32 v73, v14, v73
	v_mul_f32_e32 v70, v14, v70
	v_mul_f32_e32 v71, v14, v71
	v_mul_f32_e32 v68, v14, v68
	v_mul_f32_e32 v69, v14, v69
	v_mul_f32_e32 v66, v14, v66
	v_mul_f32_e32 v67, v14, v67
	v_mul_f32_e32 v64, v14, v64
	v_mul_f32_e32 v65, v14, v65
	v_mul_f32_e32 v62, v14, v62
	v_mul_f32_e32 v63, v14, v63
	v_mul_f32_e32 v60, v14, v60
	v_mul_f32_e32 v61, v14, v61
	v_mul_f32_e32 v58, v14, v58
	v_mul_f32_e32 v59, v14, v59
	v_mul_f32_e32 v56, v14, v56
	v_mul_f32_e32 v57, v14, v57
	v_mul_f32_e32 v54, v14, v54
	v_mul_f32_e32 v55, v14, v55
	v_mul_f32_e32 v52, v14, v52
	v_mul_f32_e32 v53, v14, v53
	v_mul_f32_e32 v50, v14, v50
	v_mul_f32_e32 v51, v14, v51
	v_mul_f32_e32 v48, v14, v48
	v_mul_f32_e32 v49, v14, v49

.LBB0_568:
	v_mov_b32_e32 v164, v168
	s_nop 1
	v_permlane32_swap_b32_e32 v168, v164
	v_max3_f32 v205, v15, v168, v164
	v_cmp_gt_f32_e32 vcc, v205, v15
	s_cbranch_vccz .LBB0_570
	v_sub_f32_e32 v15, v15, v205
	v_exp_f32_e32 v164, v15
	s_nop 0
	v_mul_f32_e32 v192, v192, v164
	v_mul_f32_e32 v46, v164, v46
	v_mul_f32_e32 v47, v164, v47
	v_mul_f32_e32 v44, v164, v44
	v_mul_f32_e32 v45, v164, v45
	v_mul_f32_e32 v42, v164, v42
	v_mul_f32_e32 v43, v164, v43
	v_mul_f32_e32 v40, v164, v40
	v_mul_f32_e32 v41, v164, v41
	v_mul_f32_e32 v38, v164, v38
	v_mul_f32_e32 v39, v164, v39
	v_mul_f32_e32 v36, v164, v36
	v_mul_f32_e32 v37, v164, v37
	v_mul_f32_e32 v34, v164, v34
	v_mul_f32_e32 v35, v164, v35
	v_mul_f32_e32 v32, v164, v32
	v_mul_f32_e32 v33, v164, v33
	v_mul_f32_e32 v30, v164, v30
	v_mul_f32_e32 v31, v164, v31
	v_mul_f32_e32 v28, v164, v28
	v_mul_f32_e32 v29, v164, v29
	v_mul_f32_e32 v26, v164, v26
	v_mul_f32_e32 v27, v164, v27
	v_mul_f32_e32 v24, v164, v24
	v_mul_f32_e32 v25, v164, v25
	v_mul_f32_e32 v22, v164, v22
	v_mul_f32_e32 v23, v164, v23
	v_mul_f32_e32 v20, v164, v20
	v_mul_f32_e32 v21, v164, v21
	v_mul_f32_e32 v18, v164, v18
	v_mul_f32_e32 v19, v164, v19
	v_mul_f32_e32 v16, v164, v16
	v_mul_f32_e32 v17, v164, v17
